# attention: lazy reference max (QK^T accumulators start at -m_ref, rescale of o/l only when a score exceeds m_ref by >8 log2 units), exp in place, no per-tile subs/o-scaling
# speedup vs baseline: 1.0158x; 1.0068x over previous
.Lattn_nosw_2:
	ds_write_b128 v188, v[20:23] offset:14336
	v_or_b32_e32 v210, v204, v79
	v_mov_b32_e32 v2, v3
	v_mov_b32_e32 v4, v3
	v_mov_b32_e32 v5, v3
	v_add_u32_e32 v212, v8, v76
	v_add_u32_e32 v213, v24, v9
	v_mov_b64_e32 v[22:23], v[6:7]
	v_mov_b64_e32 v[10:11], v[6:7]
	v_mov_b64_e32 v[26:27], v[6:7]
	v_mov_b64_e32 v[14:15], v[6:7]
	v_mov_b64_e32 v[30:31], v[6:7]
	v_mov_b64_e32 v[18:19], v[6:7]
	v_mov_b64_e32 v[98:99], v[6:7]
	s_mov_b32 s61, 3
	v_ashrrev_i32_e32 v167, 31, v166
	v_ashrrev_i32_e32 v1, 31, v0
	v_add_u32_e32 v209, 2, v205
	v_or_b32_e32 v189, 31, v204
	v_lshlrev_b32_e32 v187, 2, v83
	v_or_b32_e32 v211, 16, v210
	v_mov_b32_e32 v215, 0xf149f2ca
	s_movk_i32 s56, 0xc0
	s_mov_b64 s[54:55], 0
	v_mov_b64_e32 v[20:21], v[4:5]
	v_mov_b64_e32 v[8:9], v[4:5]
	v_mov_b64_e32 v[24:25], v[4:5]
	v_mov_b64_e32 v[12:13], v[4:5]
	v_mov_b64_e32 v[28:29], v[4:5]
	v_mov_b64_e32 v[16:17], v[4:5]
	v_mov_b64_e32 v[96:97], v[4:5]
	v_mov_b32_e32 v214, 0xf149f2ca
	v_mov_b64_e32 v[164:165], v[2:3]
	s_waitcnt lgkmcnt(0)
	s_barrier
	s_mov_b32 s101, 0xff800000
	v_mov_b32_e32 v240, 0
	v_mov_b32_e32 v241, 0
	v_mov_b32_e32 v242, 0
	v_mov_b32_e32 v243, 0
	v_mov_b32_e32 v244, 0
	v_mov_b32_e32 v245, 0
	v_mov_b32_e32 v246, 0
	v_mov_b32_e32 v247, 0
	s_branch .LBB0_856

.LBB0_858:
	s_or_b64 exec, exec, s[0:1]
	s_add_i32 s0, s56, 0xffffff40
	v_cmp_le_i32_e64 s[0:1], s0, v189
	s_and_saveexec_b64 s[40:41], s[0:1]
	s_cbranch_execz .LBB0_862
	ds_read_b128 v[100:103], v212
	ds_read_b128 v[104:107], v212 offset:64
	ds_read_b128 v[108:111], v212 offset:128
	ds_read_b128 v[112:115], v212 offset:3584
	ds_read_b128 v[116:119], v212 offset:3648
	ds_read_b128 v[120:123], v212 offset:3712
	ds_read_b128 v[124:127], v212 offset:7168
	ds_read_b128 v[128:131], v212 offset:7232
	ds_read_b128 v[132:135], v212 offset:7296
	ds_read_b128 v[216:219], v212 offset:10752
	ds_read_b128 v[220:223], v212 offset:10816
	ds_read_b128 v[224:227], v212 offset:10880
	s_waitcnt vmcnt(10) lgkmcnt(11)
	v_mfma_f32_16x16x32_bf16 v[136:139], v[100:103], v[32:35], v[240:243]
	s_waitcnt vmcnt(7)
	v_mfma_f32_16x16x32_bf16 v[100:103], v[100:103], v[44:47], v[244:247]
	s_waitcnt vmcnt(6) lgkmcnt(10)
	v_mfma_f32_16x16x32_bf16 v[100:103], v[104:107], v[48:51], v[100:103]
	s_waitcnt vmcnt(5) lgkmcnt(9)
	v_mfma_f32_16x16x32_bf16 v[144:147], v[108:111], v[52:55], v[100:103]
	s_waitcnt lgkmcnt(8)
	v_mfma_f32_16x16x32_bf16 v[100:103], v[112:115], v[32:35], v[240:243]
	s_waitcnt lgkmcnt(7)
	v_mfma_f32_16x16x32_bf16 v[100:103], v[116:119], v[36:39], v[100:103]
	s_waitcnt lgkmcnt(6)
	v_mfma_f32_16x16x32_bf16 v[156:159], v[120:123], v[40:43], v[100:103]
	v_mfma_f32_16x16x32_bf16 v[100:103], v[112:115], v[44:47], v[244:247]
	v_mfma_f32_16x16x32_bf16 v[100:103], v[116:119], v[48:51], v[100:103]
	v_mfma_f32_16x16x32_bf16 v[140:143], v[120:123], v[52:55], v[100:103]
	s_waitcnt lgkmcnt(5)
	v_mfma_f32_16x16x32_bf16 v[100:103], v[124:127], v[32:35], v[240:243]
	s_waitcnt lgkmcnt(4)
	v_mfma_f32_16x16x32_bf16 v[100:103], v[128:131], v[36:39], v[100:103]
	s_waitcnt lgkmcnt(3)
	v_mfma_f32_16x16x32_bf16 v[152:155], v[132:135], v[40:43], v[100:103]
	v_mfma_f32_16x16x32_bf16 v[100:103], v[124:127], v[44:47], v[244:247]
	v_mfma_f32_16x16x32_bf16 v[136:139], v[104:107], v[36:39], v[136:139]
	v_mfma_f32_16x16x32_bf16 v[100:103], v[128:131], v[48:51], v[100:103]
	v_mfma_f32_16x16x32_bf16 v[160:163], v[108:111], v[40:43], v[136:139]
	v_mfma_f32_16x16x32_bf16 v[136:139], v[132:135], v[52:55], v[100:103]
	s_waitcnt lgkmcnt(2)
	v_mfma_f32_16x16x32_bf16 v[100:103], v[216:219], v[32:35], v[240:243]
	s_waitcnt lgkmcnt(1)
	v_mfma_f32_16x16x32_bf16 v[100:103], v[220:223], v[36:39], v[100:103]
	s_waitcnt lgkmcnt(0)
	v_mfma_f32_16x16x32_bf16 v[148:151], v[224:227], v[40:43], v[100:103]
	v_mfma_f32_16x16x32_bf16 v[100:103], v[216:219], v[44:47], v[244:247]
	v_mfma_f32_16x16x32_bf16 v[100:103], v[220:223], v[48:51], v[100:103]
	v_mfma_f32_16x16x32_bf16 v[132:135], v[224:227], v[52:55], v[100:103]
	v_add_u32_e32 v2, 0x3800, v213
	s_nop 5
	ds_read2_b64 v[100:103], v2 offset1:4
	ds_read2_b64 v[104:107], v2 offset0:8 offset1:12
	v_add_u32_e32 v2, 0x4000, v213
	ds_read2_b64 v[108:111], v2 offset0:32 offset1:36
	ds_read2_b64 v[112:115], v2 offset0:40 offset1:44
	v_add_u32_e32 v2, 0x4800, v213
	ds_read2_b64 v[120:123], v2 offset0:64 offset1:68
	ds_read2_b64 v[124:127], v2 offset0:72 offset1:76
	v_add_u32_e32 v2, 0x5000, v213
	ds_read2_b64 v[128:131], v2 offset0:96 offset1:100
	ds_read2_b64 v[116:119], v2 offset0:104 offset1:108
	s_add_i32 s0, s56, 0xffffff7f
	v_cmp_gt_i32_e64 s[0:1], s0, v204
	s_and_saveexec_b64 s[58:59], s[0:1]
	s_cbranch_execz .LBB0_861
	v_add_u32_e32 v216, s56, v187
	v_add_u32_e32 v217, 0xffffff40, v216
	v_mov_b32_e32 v2, s29
	v_cmp_gt_i32_e64 s[0:1], v217, v210
	v_cmp_lt_i32_e64 s[42:43], v217, v210
	v_add_u32_e32 v218, 0xffffff42, v216
	v_cndmask_b32_e64 v2, v160, v2, s[0:1]
	v_cndmask_b32_e64 v160, v2, v160, s[42:43]
	v_cndmask_b32_e64 v161, v203, v161, s[42:43]
	v_cmp_le_i32_e64 s[42:43], v218, v210
	v_add_u32_e32 v219, 0xffffff43, v216
	v_mov_b32_e32 v2, s29
	v_cndmask_b32_e64 v162, v203, v162, s[42:43]
	v_cmp_le_i32_e64 s[42:43], v219, v210
	v_add_u32_e32 v220, 0xffffff63, v216
	s_nop 0
	v_cndmask_b32_e64 v163, v203, v163, s[42:43]
	v_cmp_gt_i32_e64 s[42:43], v217, v211
	s_nop 1
	v_cndmask_b32_e64 v2, v144, v2, s[42:43]
	v_cmp_lt_i32_e64 s[42:43], v217, v211
	v_add_u32_e32 v217, 0xffffff50, v216
	s_nop 0
	v_cndmask_b32_e64 v144, v2, v144, s[42:43]
	v_cndmask_b32_e64 v145, v203, v145, s[42:43]
	v_cmp_le_i32_e64 s[42:43], v218, v211
	v_mov_b32_e32 v2, s29
	v_add_u32_e32 v218, 0xffffff52, v216
	v_cndmask_b32_e64 v146, v203, v146, s[42:43]
	v_cmp_le_i32_e64 s[42:43], v219, v211
	v_cndmask_b32_e64 v140, v140, v2, s[0:1]
	v_add_u32_e32 v219, 0xffffff53, v216
	v_cndmask_b32_e64 v147, v203, v147, s[42:43]
	v_cmp_gt_i32_e64 s[42:43], v217, v210
	v_add_u32_e32 v217, 0xffffff51, v216
	v_cmp_le_i32_e64 s[0:1], v217, v211
	v_cndmask_b32_e64 v156, v156, v2, s[42:43]
	v_cmp_le_i32_e64 s[42:43], v217, v210
	v_cndmask_b32_e64 v141, v203, v141, s[0:1]
	v_cmp_le_i32_e64 s[0:1], v218, v211
	v_add_u32_e32 v217, 0xffffff60, v216
	v_cndmask_b32_e64 v157, v203, v157, s[42:43]
	v_cndmask_b32_e64 v142, v203, v142, s[0:1]
	v_cmp_le_i32_e64 s[0:1], v219, v211
	v_cmp_le_i32_e64 s[42:43], v218, v210
	v_add_u32_e32 v218, 0xffffff61, v216
	v_cndmask_b32_e64 v143, v203, v143, s[0:1]
	v_cmp_gt_i32_e64 s[0:1], v217, v210
	v_cndmask_b32_e64 v158, v203, v158, s[42:43]
	v_cmp_le_i32_e64 s[42:43], v219, v210
	v_cndmask_b32_e64 v152, v152, v2, s[0:1]
	v_cmp_le_i32_e64 s[0:1], v218, v210
	v_add_u32_e32 v219, 0xffffff62, v216
	v_cndmask_b32_e64 v159, v203, v159, s[42:43]
	v_cndmask_b32_e64 v153, v203, v153, s[0:1]
	v_cmp_le_i32_e64 s[0:1], v219, v210
	s_nop 1
	v_cndmask_b32_e64 v154, v203, v154, s[0:1]
	v_cmp_le_i32_e64 s[0:1], v220, v210
	s_nop 1
	v_cndmask_b32_e64 v155, v203, v155, s[0:1]
	v_cmp_gt_i32_e64 s[0:1], v217, v211
	v_add_u32_e32 v217, 0xffffff70, v216
	s_nop 0
	v_cndmask_b32_e64 v136, v136, v2, s[0:1]
	v_cmp_le_i32_e64 s[0:1], v218, v211
	v_add_u32_e32 v218, 0xffffff71, v216
	s_nop 0
	v_cndmask_b32_e64 v137, v203, v137, s[0:1]
	v_cmp_le_i32_e64 s[0:1], v219, v211
	v_add_u32_e32 v219, 0xffffff72, v216
	v_add_u32_e32 v216, 0xffffff73, v216
	v_cndmask_b32_e64 v138, v203, v138, s[0:1]
	v_cmp_le_i32_e64 s[0:1], v220, v211
	s_nop 1
	v_cndmask_b32_e64 v139, v203, v139, s[0:1]
	v_cmp_gt_i32_e64 s[0:1], v217, v210
	s_nop 1
	v_cndmask_b32_e64 v148, v148, v2, s[0:1]
	v_cmp_le_i32_e64 s[0:1], v218, v210
	s_nop 1
	v_cndmask_b32_e64 v149, v203, v149, s[0:1]
	v_cmp_le_i32_e64 s[0:1], v219, v210
	s_nop 1
	v_cndmask_b32_e64 v150, v203, v150, s[0:1]
	v_cmp_le_i32_e64 s[0:1], v216, v210
	s_nop 1
	v_cndmask_b32_e64 v151, v203, v151, s[0:1]
	v_cmp_gt_i32_e64 s[0:1], v217, v211
	s_nop 1
	v_cndmask_b32_e64 v132, v132, v2, s[0:1]
	v_cmp_le_i32_e64 s[0:1], v218, v211
	s_nop 1
	v_cndmask_b32_e64 v133, v203, v133, s[0:1]
	v_cmp_le_i32_e64 s[0:1], v219, v211
	s_nop 1
	v_cndmask_b32_e64 v134, v203, v134, s[0:1]
	v_cmp_le_i32_e64 s[0:1], v216, v211
	s_nop 1
	v_cndmask_b32_e64 v135, v203, v135, s[0:1]
.LBB0_861:
	s_or_b64 exec, exec, s[58:59]
	s_cmp_lg_u32 s101, 0
	s_cbranch_scc1 .Lal1_slow
	v_max3_f32 v216, v160, v161, v162
	v_max3_f32 v217, v163, v156, v157
	v_max3_f32 v218, v158, v159, v152
	v_max3_f32 v219, v153, v154, v155
	v_max3_f32 v220, v148, v149, v150
	v_max3_f32 v221, v151, v144, v145
	v_max3_f32 v222, v146, v147, v140
	v_max3_f32 v223, v141, v142, v143
	v_max3_f32 v224, v136, v137, v138
	v_max3_f32 v225, v139, v132, v133
	v_max3_f32 v226, v216, v217, v218
	v_max3_f32 v227, v219, v220, v221
	v_max3_f32 v228, v222, v223, v224
	v_max3_f32 v229, v225, v134, v135
	v_max3_f32 v230, v226, v227, v228
	v_max_f32_e32 v230, v230, v229
	s_nop 0
	s_mov_b32 s42, 0x41000000
	v_cmp_lt_f32_e64 s[42:43], s42, v230
	s_cmp_lg_u64 s[42:43], 0
	s_cbranch_scc0 .Lal1_fast
.Lal1_slow:
	v_max3_f32 v220, v160, v161, v162
	v_max3_f32 v221, v163, v156, v157
	v_max3_f32 v222, v158, v159, v152
	v_max3_f32 v223, v153, v154, v155
	v_max3_f32 v224, v148, v149, v150
	v_max3_f32 v225, v220, v221, v222
	v_max3_f32 v226, v223, v224, v151
	v_max_f32_e32 v216, v225, v226
	s_nop 0
	v_mov_b32_e32 v217, v216
	s_nop 1
	v_permlane16_swap_b32_e32 v216, v217
	s_nop 1
	v_max_f32_e32 v216, v216, v217
	s_nop 0
	v_mov_b32_e32 v217, v216
	s_nop 1
	v_permlane32_swap_b32_e32 v216, v217
	s_nop 1
	v_max_f32_e32 v216, v216, v217
	v_max3_f32 v220, v144, v145, v146
	v_max3_f32 v221, v147, v140, v141
	v_max3_f32 v222, v142, v143, v136
	v_max3_f32 v223, v137, v138, v139
	v_max3_f32 v224, v132, v133, v134
	v_max3_f32 v225, v220, v221, v222
	v_max3_f32 v226, v223, v224, v135
	v_max_f32_e32 v218, v225, v226
	s_nop 0
	v_mov_b32_e32 v219, v218
	s_nop 1
	v_permlane16_swap_b32_e32 v218, v219
	s_nop 1
	v_max_f32_e32 v218, v218, v219
	s_nop 0
	v_mov_b32_e32 v219, v218
	s_nop 1
	v_permlane32_swap_b32_e32 v218, v219
	s_nop 1
	v_max_f32_e32 v218, v218, v219
	s_nop 0
	v_max_f32_e32 v216, s101, v216
	v_max_f32_e32 v218, s101, v218
	s_nop 0
	v_min_f32_e64 v220, -v216, 0
	v_min_f32_e64 v221, -v218, 0
	s_nop 0
	v_exp_f32_e32 v228, v220
	v_exp_f32_e32 v230, v221
	v_sub_f32_e32 v240, v240, v216
	v_sub_f32_e32 v241, v241, v216
	v_sub_f32_e32 v242, v242, v216
	v_sub_f32_e32 v243, v243, v216
	v_sub_f32_e32 v244, v244, v218
	v_sub_f32_e32 v245, v245, v218
	v_sub_f32_e32 v246, v246, v218
	v_sub_f32_e32 v247, v247, v218
	v_sub_f32_e32 v160, v160, v216
	v_sub_f32_e32 v161, v161, v216
	v_sub_f32_e32 v162, v162, v216
	v_sub_f32_e32 v163, v163, v216
	v_sub_f32_e32 v156, v156, v216
	v_sub_f32_e32 v157, v157, v216
	v_sub_f32_e32 v158, v158, v216
	v_sub_f32_e32 v159, v159, v216
	v_sub_f32_e32 v152, v152, v216
	v_sub_f32_e32 v153, v153, v216
	v_sub_f32_e32 v154, v154, v216
	v_sub_f32_e32 v155, v155, v216
	v_sub_f32_e32 v148, v148, v216
	v_sub_f32_e32 v149, v149, v216
	v_sub_f32_e32 v150, v150, v216
	v_sub_f32_e32 v151, v151, v216
	v_sub_f32_e32 v144, v144, v218
	v_sub_f32_e32 v145, v145, v218
	v_sub_f32_e32 v146, v146, v218
	v_sub_f32_e32 v147, v147, v218
	v_sub_f32_e32 v140, v140, v218
	v_sub_f32_e32 v141, v141, v218
	v_sub_f32_e32 v142, v142, v218
	v_sub_f32_e32 v143, v143, v218
	v_sub_f32_e32 v136, v136, v218
	v_sub_f32_e32 v137, v137, v218
	v_sub_f32_e32 v138, v138, v218
	v_sub_f32_e32 v139, v139, v218
	v_sub_f32_e32 v132, v132, v218
	v_sub_f32_e32 v133, v133, v218
	v_sub_f32_e32 v134, v134, v218
	v_sub_f32_e32 v135, v135, v218
	v_pk_mul_f32 v[96:97], v[96:97], v[228:229] op_sel_hi:[1,0]
	v_pk_mul_f32 v[98:99], v[98:99], v[228:229] op_sel_hi:[1,0]
	v_pk_mul_f32 v[28:29], v[28:29], v[228:229] op_sel_hi:[1,0]
	v_pk_mul_f32 v[30:31], v[30:31], v[228:229] op_sel_hi:[1,0]
	v_pk_mul_f32 v[24:25], v[24:25], v[228:229] op_sel_hi:[1,0]
	v_pk_mul_f32 v[26:27], v[26:27], v[228:229] op_sel_hi:[1,0]
	v_pk_mul_f32 v[20:21], v[20:21], v[228:229] op_sel_hi:[1,0]
	v_pk_mul_f32 v[22:23], v[22:23], v[228:229] op_sel_hi:[1,0]
	v_pk_mul_f32 v[16:17], v[16:17], v[230:231] op_sel_hi:[1,0]
	v_pk_mul_f32 v[18:19], v[18:19], v[230:231] op_sel_hi:[1,0]
	v_pk_mul_f32 v[12:13], v[12:13], v[230:231] op_sel_hi:[1,0]
	v_pk_mul_f32 v[14:15], v[14:15], v[230:231] op_sel_hi:[1,0]
	v_pk_mul_f32 v[8:9], v[8:9], v[230:231] op_sel_hi:[1,0]
	v_pk_mul_f32 v[10:11], v[10:11], v[230:231] op_sel_hi:[1,0]
	v_pk_mul_f32 v[4:5], v[4:5], v[230:231] op_sel_hi:[1,0]
	v_pk_mul_f32 v[6:7], v[6:7], v[230:231] op_sel_hi:[1,0]
	v_mul_f32_e32 v165, v165, v228
	v_mul_f32_e32 v164, v164, v230
	s_mov_b32 s101, 0
.Lal1_fast:
	v_exp_f32_e32 v160, v160
	v_exp_f32_e32 v144, v144
	v_exp_f32_e32 v161, v161
	v_exp_f32_e32 v145, v145
	v_add_f32_e32 v165, v165, v160
	v_add_f32_e32 v164, v164, v144
	v_exp_f32_e32 v162, v162
	v_exp_f32_e32 v146, v146
	v_add_f32_e32 v165, v165, v161
	v_add_f32_e32 v164, v164, v145
	v_exp_f32_e32 v163, v163
	v_exp_f32_e32 v147, v147
	v_add_f32_e32 v165, v165, v162
	v_add_f32_e32 v164, v164, v146
	v_exp_f32_e32 v156, v156
	v_exp_f32_e32 v140, v140
	v_add_f32_e32 v165, v165, v163
	v_add_f32_e32 v164, v164, v147
	v_exp_f32_e32 v157, v157
	v_exp_f32_e32 v141, v141
	v_add_f32_e32 v165, v165, v156
	v_add_f32_e32 v164, v164, v140
	v_exp_f32_e32 v158, v158
	v_exp_f32_e32 v142, v142
	v_add_f32_e32 v165, v165, v157
	v_add_f32_e32 v164, v164, v141
	v_exp_f32_e32 v159, v159
	v_exp_f32_e32 v143, v143
	v_add_f32_e32 v165, v165, v158
	v_add_f32_e32 v164, v164, v142
	v_exp_f32_e32 v152, v152
	v_exp_f32_e32 v136, v136
	v_add_f32_e32 v165, v165, v159
	v_add_f32_e32 v164, v164, v143
	v_exp_f32_e32 v153, v153
	v_exp_f32_e32 v137, v137
	v_add_f32_e32 v165, v165, v152
	v_add_f32_e32 v164, v164, v136
	v_exp_f32_e32 v154, v154
	v_exp_f32_e32 v138, v138
	v_add_f32_e32 v165, v165, v153
	v_add_f32_e32 v164, v164, v137
	v_exp_f32_e32 v155, v155
	v_exp_f32_e32 v139, v139
	v_add_f32_e32 v165, v165, v154
	v_add_f32_e32 v164, v164, v138
	v_exp_f32_e32 v148, v148
	v_exp_f32_e32 v132, v132
	v_add_f32_e32 v165, v165, v155
	v_add_f32_e32 v164, v164, v139
	v_exp_f32_e32 v149, v149
	v_exp_f32_e32 v133, v133
	v_add_f32_e32 v165, v165, v148
	v_add_f32_e32 v164, v164, v132
	v_exp_f32_e32 v150, v150
	v_exp_f32_e32 v134, v134
	v_add_f32_e32 v165, v165, v149
	v_add_f32_e32 v164, v164, v133
	v_exp_f32_e32 v151, v151
	v_exp_f32_e32 v135, v135
	v_add_f32_e32 v165, v165, v150
	v_add_f32_e32 v164, v164, v134
	s_nop 0
	v_add_f32_e32 v165, v165, v151
	v_add_f32_e32 v164, v164, v135
	v_cvt_pk_bf16_f32 v160, v160, v161
	v_cvt_pk_bf16_f32 v161, v162, v163
	v_cvt_pk_bf16_f32 v162, v156, v157
	v_cvt_pk_bf16_f32 v163, v158, v159
	v_cvt_pk_bf16_f32 v144, v144, v145
	v_cvt_pk_bf16_f32 v145, v146, v147
	v_cvt_pk_bf16_f32 v146, v140, v141
	v_cvt_pk_bf16_f32 v147, v142, v143
	v_cvt_pk_bf16_f32 v152, v152, v153
	v_cvt_pk_bf16_f32 v153, v154, v155
	v_cvt_pk_bf16_f32 v154, v148, v149
	v_cvt_pk_bf16_f32 v155, v150, v151
	v_cvt_pk_bf16_f32 v136, v136, v137
	v_cvt_pk_bf16_f32 v137, v138, v139
	v_cvt_pk_bf16_f32 v138, v132, v133
	v_cvt_pk_bf16_f32 v139, v134, v135
	s_nop 1
	s_waitcnt lgkmcnt(0)
	v_mfma_f32_16x16x32_bf16 v[96:99], v[100:103], v[160:163], v[96:99]
	v_mfma_f32_16x16x32_bf16 v[16:19], v[100:103], v[144:147], v[16:19]
	v_mfma_f32_16x16x32_bf16 v[28:31], v[108:111], v[160:163], v[28:31]
	v_mfma_f32_16x16x32_bf16 v[12:15], v[108:111], v[144:147], v[12:15]
	v_mfma_f32_16x16x32_bf16 v[24:27], v[120:123], v[160:163], v[24:27]
	v_mfma_f32_16x16x32_bf16 v[8:11], v[120:123], v[144:147], v[8:11]
	v_mfma_f32_16x16x32_bf16 v[20:23], v[128:131], v[160:163], v[20:23]
	v_mfma_f32_16x16x32_bf16 v[4:7], v[128:131], v[144:147], v[4:7]
	v_mfma_f32_16x16x32_bf16 v[96:99], v[104:107], v[152:155], v[96:99]
	v_mfma_f32_16x16x32_bf16 v[16:19], v[104:107], v[136:139], v[16:19]
	v_mfma_f32_16x16x32_bf16 v[28:31], v[112:115], v[152:155], v[28:31]
	v_mfma_f32_16x16x32_bf16 v[12:15], v[112:115], v[136:139], v[12:15]
	v_mfma_f32_16x16x32_bf16 v[24:27], v[124:127], v[152:155], v[24:27]
	v_mfma_f32_16x16x32_bf16 v[8:11], v[124:127], v[136:139], v[8:11]
	v_mfma_f32_16x16x32_bf16 v[20:23], v[116:119], v[152:155], v[20:23]
	v_mfma_f32_16x16x32_bf16 v[4:7], v[116:119], v[136:139], v[4:7]

.LBB0_864:
	s_or_b64 exec, exec, s[12:13]
	s_add_i32 s0, s56, 0xffffff80
	v_cmp_le_i32_e64 s[0:1], s0, v189
	s_and_saveexec_b64 s[40:41], s[0:1]
	s_cbranch_execz .LBB0_868
	ds_read_b128 v[100:103], v212 offset:23616
	ds_read_b128 v[104:107], v212 offset:23680
	ds_read_b128 v[108:111], v212 offset:27136
	ds_read_b128 v[112:115], v212 offset:27200
	ds_read_b128 v[116:119], v212 offset:27264
	ds_read_b128 v[120:123], v212 offset:30720
	ds_read_b128 v[124:127], v212 offset:30784
	ds_read_b128 v[128:131], v212 offset:30848
	ds_read_b128 v[132:135], v212 offset:34304
	ds_read_b128 v[216:219], v212 offset:34368
	ds_read_b128 v[136:139], v212 offset:23552
	ds_read_b128 v[220:223], v212 offset:34432
	s_waitcnt lgkmcnt(1)
	v_mfma_f32_16x16x32_bf16 v[140:143], v[136:139], v[32:35], v[240:243]
	v_mfma_f32_16x16x32_bf16 v[136:139], v[136:139], v[44:47], v[244:247]
	v_mfma_f32_16x16x32_bf16 v[140:143], v[100:103], v[36:39], v[140:143]
	v_mfma_f32_16x16x32_bf16 v[100:103], v[100:103], v[48:51], v[136:139]
	v_mfma_f32_16x16x32_bf16 v[144:147], v[104:107], v[52:55], v[100:103]
	v_mfma_f32_16x16x32_bf16 v[100:103], v[108:111], v[32:35], v[240:243]
	v_mfma_f32_16x16x32_bf16 v[100:103], v[112:115], v[36:39], v[100:103]
	v_mfma_f32_16x16x32_bf16 v[156:159], v[116:119], v[40:43], v[100:103]
	v_mfma_f32_16x16x32_bf16 v[100:103], v[108:111], v[44:47], v[244:247]
	v_mfma_f32_16x16x32_bf16 v[100:103], v[112:115], v[48:51], v[100:103]
	v_mfma_f32_16x16x32_bf16 v[160:163], v[104:107], v[40:43], v[140:143]
	v_mfma_f32_16x16x32_bf16 v[140:143], v[116:119], v[52:55], v[100:103]
	v_mfma_f32_16x16x32_bf16 v[100:103], v[120:123], v[32:35], v[240:243]
	v_mfma_f32_16x16x32_bf16 v[100:103], v[124:127], v[36:39], v[100:103]
	v_mfma_f32_16x16x32_bf16 v[152:155], v[128:131], v[40:43], v[100:103]
	v_mfma_f32_16x16x32_bf16 v[100:103], v[120:123], v[44:47], v[244:247]
	v_mfma_f32_16x16x32_bf16 v[100:103], v[124:127], v[48:51], v[100:103]
	v_mfma_f32_16x16x32_bf16 v[136:139], v[128:131], v[52:55], v[100:103]
	v_mfma_f32_16x16x32_bf16 v[100:103], v[132:135], v[32:35], v[240:243]
	v_mfma_f32_16x16x32_bf16 v[100:103], v[216:219], v[36:39], v[100:103]
	s_waitcnt lgkmcnt(0)
	v_mfma_f32_16x16x32_bf16 v[148:151], v[220:223], v[40:43], v[100:103]
	v_mfma_f32_16x16x32_bf16 v[100:103], v[132:135], v[44:47], v[244:247]
	v_mfma_f32_16x16x32_bf16 v[100:103], v[216:219], v[48:51], v[100:103]
	v_mfma_f32_16x16x32_bf16 v[132:135], v[220:223], v[52:55], v[100:103]
	v_add_u32_e32 v2, 0x9000, v213
	s_nop 5
	ds_read2_b64 v[100:103], v2 offset0:128 offset1:132
	ds_read2_b64 v[104:107], v2 offset0:136 offset1:140
	v_add_u32_e32 v2, 0x9800, v213
	ds_read2_b64 v[108:111], v2 offset0:160 offset1:164
	ds_read2_b64 v[112:115], v2 offset0:168 offset1:172
	v_add_u32_e32 v2, 0xa000, v213
	ds_read2_b64 v[120:123], v2 offset0:192 offset1:196
	ds_read2_b64 v[124:127], v2 offset0:200 offset1:204
	v_add_u32_e32 v2, 0xa800, v213
	ds_read2_b64 v[128:131], v2 offset0:224 offset1:228
	ds_read2_b64 v[116:119], v2 offset0:232 offset1:236
	s_add_i32 s0, s56, 0xffffffbf
	v_cmp_gt_i32_e64 s[0:1], s0, v204
	s_and_saveexec_b64 s[58:59], s[0:1]
	s_cbranch_execz .LBB0_867
	v_add_u32_e32 v216, s56, v187
	v_add_u32_e32 v217, 0xffffff80, v216
	v_mov_b32_e32 v2, s29
	v_cmp_gt_i32_e64 s[0:1], v217, v210
	v_cmp_lt_i32_e64 s[42:43], v217, v210
	v_add_u32_e32 v218, 0xffffff82, v216
	v_cndmask_b32_e64 v2, v160, v2, s[0:1]
	v_cndmask_b32_e64 v160, v2, v160, s[42:43]
	v_cndmask_b32_e64 v161, v203, v161, s[42:43]
	v_cmp_le_i32_e64 s[42:43], v218, v210
	v_add_u32_e32 v219, 0xffffff83, v216
	v_mov_b32_e32 v2, s29
	v_cndmask_b32_e64 v162, v203, v162, s[42:43]
	v_cmp_le_i32_e64 s[42:43], v219, v210
	v_add_u32_e32 v220, 0xffffffa3, v216
	s_nop 0
	v_cndmask_b32_e64 v163, v203, v163, s[42:43]
	v_cmp_gt_i32_e64 s[42:43], v217, v211
	s_nop 1
	v_cndmask_b32_e64 v2, v144, v2, s[42:43]
	v_cmp_lt_i32_e64 s[42:43], v217, v211
	v_add_u32_e32 v217, 0xffffff90, v216
	s_nop 0
	v_cndmask_b32_e64 v144, v2, v144, s[42:43]
	v_cndmask_b32_e64 v145, v203, v145, s[42:43]
	v_cmp_le_i32_e64 s[42:43], v218, v211
	v_mov_b32_e32 v2, s29
	v_add_u32_e32 v218, 0xffffff92, v216
	v_cndmask_b32_e64 v146, v203, v146, s[42:43]
	v_cmp_le_i32_e64 s[42:43], v219, v211
	v_cndmask_b32_e64 v140, v140, v2, s[0:1]
	v_add_u32_e32 v219, 0xffffff93, v216
	v_cndmask_b32_e64 v147, v203, v147, s[42:43]
	v_cmp_gt_i32_e64 s[42:43], v217, v210
	v_add_u32_e32 v217, 0xffffff91, v216
	v_cmp_le_i32_e64 s[0:1], v217, v211
	v_cndmask_b32_e64 v156, v156, v2, s[42:43]
	v_cmp_le_i32_e64 s[42:43], v217, v210
	v_cndmask_b32_e64 v141, v203, v141, s[0:1]
	v_cmp_le_i32_e64 s[0:1], v218, v211
	v_add_u32_e32 v217, 0xffffffa0, v216
	v_cndmask_b32_e64 v157, v203, v157, s[42:43]
	v_cndmask_b32_e64 v142, v203, v142, s[0:1]
	v_cmp_le_i32_e64 s[0:1], v219, v211
	v_cmp_le_i32_e64 s[42:43], v218, v210
	v_add_u32_e32 v218, 0xffffffa1, v216
	v_cndmask_b32_e64 v143, v203, v143, s[0:1]
	v_cmp_gt_i32_e64 s[0:1], v217, v210
	v_cndmask_b32_e64 v158, v203, v158, s[42:43]
	v_cmp_le_i32_e64 s[42:43], v219, v210
	v_cndmask_b32_e64 v152, v152, v2, s[0:1]
	v_cmp_le_i32_e64 s[0:1], v218, v210
	v_add_u32_e32 v219, 0xffffffa2, v216
	v_cndmask_b32_e64 v159, v203, v159, s[42:43]
	v_cndmask_b32_e64 v153, v203, v153, s[0:1]
	v_cmp_le_i32_e64 s[0:1], v219, v210
	s_nop 1
	v_cndmask_b32_e64 v154, v203, v154, s[0:1]
	v_cmp_le_i32_e64 s[0:1], v220, v210
	s_nop 1
	v_cndmask_b32_e64 v155, v203, v155, s[0:1]
	v_cmp_gt_i32_e64 s[0:1], v217, v211
	v_add_u32_e32 v217, 0xffffffb0, v216
	s_nop 0
	v_cndmask_b32_e64 v136, v136, v2, s[0:1]
	v_cmp_le_i32_e64 s[0:1], v218, v211
	v_add_u32_e32 v218, 0xffffffb1, v216
	s_nop 0
	v_cndmask_b32_e64 v137, v203, v137, s[0:1]
	v_cmp_le_i32_e64 s[0:1], v219, v211
	v_add_u32_e32 v219, 0xffffffb2, v216
	v_add_u32_e32 v216, 0xffffffb3, v216
	v_cndmask_b32_e64 v138, v203, v138, s[0:1]
	v_cmp_le_i32_e64 s[0:1], v220, v211
	s_nop 1
	v_cndmask_b32_e64 v139, v203, v139, s[0:1]
	v_cmp_gt_i32_e64 s[0:1], v217, v210
	s_nop 1
	v_cndmask_b32_e64 v148, v148, v2, s[0:1]
	v_cmp_le_i32_e64 s[0:1], v218, v210
	s_nop 1
	v_cndmask_b32_e64 v149, v203, v149, s[0:1]
	v_cmp_le_i32_e64 s[0:1], v219, v210
	s_nop 1
	v_cndmask_b32_e64 v150, v203, v150, s[0:1]
	v_cmp_le_i32_e64 s[0:1], v216, v210
	s_nop 1
	v_cndmask_b32_e64 v151, v203, v151, s[0:1]
	v_cmp_gt_i32_e64 s[0:1], v217, v211
	s_nop 1
	v_cndmask_b32_e64 v132, v132, v2, s[0:1]
	v_cmp_le_i32_e64 s[0:1], v218, v211
	s_nop 1
	v_cndmask_b32_e64 v133, v203, v133, s[0:1]
	v_cmp_le_i32_e64 s[0:1], v219, v211
	s_nop 1
	v_cndmask_b32_e64 v134, v203, v134, s[0:1]
	v_cmp_le_i32_e64 s[0:1], v216, v211
	s_nop 1
	v_cndmask_b32_e64 v135, v203, v135, s[0:1]

	.amdhsa_kernel _Z14fwd_megakernel6Params
		.amdhsa_group_segment_fixed_size 65856
		.amdhsa_private_segment_fixed_size 0
		.amdhsa_kernarg_size 488
		.amdhsa_user_sgpr_count 2
		.amdhsa_user_sgpr_dispatch_ptr 0
		.amdhsa_user_sgpr_queue_ptr 0
		.amdhsa_user_sgpr_kernarg_segment_ptr 1
		.amdhsa_user_sgpr_dispatch_id 0
		.amdhsa_user_sgpr_kernarg_preload_length 0
		.amdhsa_user_sgpr_kernarg_preload_offset 0
		.amdhsa_user_sgpr_private_segment_size 0
		.amdhsa_uses_dynamic_stack 0
		.amdhsa_enable_private_segment 0
		.amdhsa_system_sgpr_workgroup_id_x 1
		.amdhsa_system_sgpr_workgroup_id_y 0
		.amdhsa_system_sgpr_workgroup_id_z 0
		.amdhsa_system_sgpr_workgroup_info 0
		.amdhsa_system_vgpr_workitem_id 2
		.amdhsa_next_free_vgpr 256
		.amdhsa_next_free_sgpr 102
		.amdhsa_accum_offset 256
		.amdhsa_reserve_vcc 1
		.amdhsa_float_round_mode_32 0
		.amdhsa_float_round_mode_16_64 0
		.amdhsa_float_denorm_mode_32 3
		.amdhsa_float_denorm_mode_16_64 3
		.amdhsa_dx10_clamp 1
		.amdhsa_ieee_mode 1
		.amdhsa_fp16_overflow 0
		.amdhsa_tg_split 0
		.amdhsa_exception_fp_ieee_invalid_op 0
		.amdhsa_exception_fp_denorm_src 0
		.amdhsa_exception_fp_ieee_div_zero 0
		.amdhsa_exception_fp_ieee_overflow 0
		.amdhsa_exception_fp_ieee_underflow 0
		.amdhsa_exception_fp_ieee_inexact 0
		.amdhsa_exception_int_div_zero 0
	.end_amdhsa_kernel

.Lfunc_end0:
	.size	_Z14fwd_megakernel6Params, .Lfunc_end0-_Z14fwd_megakernel6Params
	.set _Z14fwd_megakernel6Params.num_vgpr, 256
	.set _Z14fwd_megakernel6Params.num_agpr, 0
	.set _Z14fwd_megakernel6Params.numbered_sgpr, 100
	.set _Z14fwd_megakernel6Params.num_named_barrier, 0
	.set _Z14fwd_megakernel6Params.private_seg_size, 0
	.set _Z14fwd_megakernel6Params.uses_vcc, 1
	.set _Z14fwd_megakernel6Params.uses_flat_scratch, 0
	.set _Z14fwd_megakernel6Params.has_dyn_sized_stack, 0
	.set _Z14fwd_megakernel6Params.has_recursion, 0
	.set _Z14fwd_megakernel6Params.has_indirect_call, 0

amdhsa.kernels:
  - .agpr_count:     0
    .args:
      - .offset:         0
        .size:           232
        .value_kind:     by_value
      - .offset:         232
        .size:           4
        .value_kind:     hidden_block_count_x
      - .offset:         236
        .size:           4
        .value_kind:     hidden_block_count_y
      - .offset:         240
        .size:           4
        .value_kind:     hidden_block_count_z
      - .offset:         244
        .size:           2
        .value_kind:     hidden_group_size_x
      - .offset:         246
        .size:           2
        .value_kind:     hidden_group_size_y
      - .offset:         248
        .size:           2
        .value_kind:     hidden_group_size_z
      - .offset:         250
        .size:           2
        .value_kind:     hidden_remainder_x
      - .offset:         252
        .size:           2
        .value_kind:     hidden_remainder_y
      - .offset:         254
        .size:           2
        .value_kind:     hidden_remainder_z
      - .offset:         272
        .size:           8
        .value_kind:     hidden_global_offset_x
      - .offset:         280
        .size:           8
        .value_kind:     hidden_global_offset_y
      - .offset:         288
        .size:           8
        .value_kind:     hidden_global_offset_z
      - .offset:         296
        .size:           2
        .value_kind:     hidden_grid_dims
      - .offset:         320
        .size:           8
        .value_kind:     hidden_multigrid_sync_arg
    .group_segment_fixed_size: 65856
    .kernarg_segment_align: 8
    .kernarg_segment_size: 488
    .language:       OpenCL C
    .language_version:
      - 2
      - 0
    .max_flat_workgroup_size: 256
    .name:           _Z14fwd_megakernel6Params
    .private_segment_fixed_size: 0
    .sgpr_count:     108
    .sgpr_spill_count: 316
    .symbol:         _Z14fwd_megakernel6Params.kd
    .uniform_work_group_size: 1
    .uses_dynamic_stack: false
    .vgpr_count:     256
    .vgpr_spill_count: 0
    .wavefront_size: 64
